# v22 + the cross-XCD completion is polled asynchronously at phase entry and only re-polled at the first epilogue if it was not complete yet
# baseline (speedup 1.0000x reference)
; #define LAS __attribute__((address_space(3)))
; #define STAGGER(ticks) do { const unsigned long long t0_ = __builtin_amdgcn_s_memrealtime(); const unsigned long long d_ = (unsigned long long)((bx >> 3) & 15) * (ticks); while (__builtin_amdgcn_s_memrealtime() - t0_ < d_) __builtin_amdgcn_s_sleep(8); } while (0)
; #define OPAQUE_TID() int tid = MYTID(); asm volatile("" : "+v"(tid)); const int lane = tid & 63, wave = __builtin_amdgcn_readfirstlane(tid >> 6); (void)lane; (void)wave
; __global__ void __launch_bounds__(NTHREADS, 2) fwd_kernel(Args a) {
;     ...
;     if (IN(3)) {
;         STAGGER(PROJ_STAGGER_TICKS);
;         pg8::Gemm g{P_XB, (const bf16_t*)(ws + WS_WIN), MTOK, NIN, DM}; pg8::StaticOrder S; S.init(MTOK, NIN, G, bx);
;         pg8::EpiProj E; unsigned char* A = ws + WS_A;
;         E.P.QA = (bf16_t*)(A + A_QA); E.P.KC = (bf16_t*)(A + A_KC); E.P.VC = (bf16_t*)(A + A_VC); E.P.KS = (bf16_t*)(A + A_KS); E.P.VS = (bf16_t*)(A + A_VS); E.P.KW = (bf16_t*)(A + A_KW); E.P.VW = (bf16_t*)(A + A_VW);
;         E.P.QB = (bf16_t*)(A + A_QB); E.P.KB = (bf16_t*)(A + A_KB); E.P.VB = (bf16_t*)(A + A_VB); E.P.GM = P_GM; E.P.GA = (float*)(ws + WS_GA); E.P.LF = (float*)(ws + WS_LF);
;         E.rt = (const LAS float*)(lds + RT_OFF); E.gt = (const LAS float*)(lds + RT_OFF + 11264);
;         { OPAQUE_TID(); LAS float* gt_ = (LAS float*)(lds + RT_OFF + 11264);
;           if (tid < 64) { gt_[tid] = a.in[7][tid]; gt_[64 + tid] = a.in[8][64 + tid]; gt_[128 + tid] = a.in[8][128 + tid]; gt_[192 + tid] = a.in[9][tid]; gt_[256 + tid] = a.in[10][tid]; if (tid < 8) gt_[320 + tid] = a.in[6][tid]; } }
.LBB0_546:
	s_cmp_lt_i32 s42, 4
	s_cselect_b64 s[0:1], -1, 0
	s_and_b64 s[8:9], s[0:1], s[2:3]
	s_andn2_b64 vcc, exec, s[8:9]
	s_cbranch_vccnz .LBB0_688
	v_mov_b32_e32 v246, 0x3500
	global_load_dword v247, v246, s[40:41] sc1
	s_memrealtime s[0:1]
	s_waitcnt lgkmcnt(0)
	s_memrealtime s[0:1]
	v_mbcnt_hi_u32_b32 v0, -1, v230
	s_waitcnt lgkmcnt(0)
	v_readlane_b32 s0, v248, 0
	s_nop 1
	v_add_u32_e32 v8, s0, v0
	v_mov_b32_e32 v0, v8
	s_nop 0
	v_cmp_gt_i32_e32 vcc, 64, v0
	s_and_saveexec_b64 s[2:3], vcc
	s_cbranch_execz .LBB0_550
	s_load_dwordx8 s[12:19], s[90:91], 0x38
	v_ashrrev_i32_e32 v1, 31, v0
	v_lshlrev_b64 v[2:3], 2, v[0:1]
	v_cmp_gt_i32_e32 vcc, 8, v0
	s_waitcnt lgkmcnt(0)
	v_lshl_add_u64 v[4:5], s[12:13], 0, v[2:3]
	v_lshl_add_u64 v[6:7], s[14:15], 0, v[2:3]
	global_load_dword v9, v[4:5], off
	global_load_dword v10, v[6:7], off offset:256
	global_load_dword v11, v[6:7], off offset:512
	v_lshl_add_u64 v[4:5], s[16:17], 0, v[2:3]
	global_load_dword v4, v[4:5], off
	v_lshl_add_u64 v[2:3], s[18:19], 0, v[2:3]
	global_load_dword v3, v[2:3], off
	v_lshl_add_u32 v2, v0, 2, 0
	v_add_u32_e32 v2, 0x22d00, v2
	s_waitcnt vmcnt(0)
	ds_write2st64_b32 v2, v9, v10 offset1:1
	ds_write2st64_b32 v2, v11, v4 offset0:2 offset1:3
	ds_write_b32 v2, v3 offset:1024
	s_and_b64 exec, exec, vcc
	s_cbranch_execz .LBB0_550
	s_load_dwordx2 s[0:1], s[90:91], 0x30
	s_waitcnt lgkmcnt(0)
	v_lshl_add_u64 v[0:1], v[0:1], 2, s[0:1]
	global_load_dword v0, v[0:1], off
	s_waitcnt vmcnt(0)
	ds_write_b32 v2, v0 offset:1280

; #define PG8_STAGE(bufoff, gbase, voff) do { _Pragma("unroll") for (int _i = 0; _i < 2; ++_i) \
;         __builtin_amdgcn_global_load_lds((const unsigned*)((const char*)(gbase) + (voff)[_i]), (PG8_LAS unsigned*)(lds + (bufoff) + ldsw + _i * 8192), 16, 0, 0); } while (0)
; #define PG8_LDA(dst, b, h) do { _Pragma("unroll") for (int m = 0; m < 4; ++m) _Pragma("unroll") for (int k = 0; k < 2; ++k) dst[m][k] = *(const PG8_LAS bf16x8*)(lds + PG8_SA(b, h) + aoff + m * 2048 + k * 1024); } while (0)
; #define PG8_LDB(dst, b, h) do { _Pragma("unroll") for (int n = 0; n < 2; ++n) _Pragma("unroll") for (int k = 0; k < 2; ++k) dst[n][k] = *(const PG8_LAS bf16x8*)(lds + PG8_SB(b, h) + boff + n * 2048 + k * 1024); } while (0)
; #define PG8_MMA(ai, bj, At, Bt) do { __builtin_amdgcn_s_setprio(1); _Pragma("unroll") for (int m = 0; m < 4; ++m) _Pragma("unroll") for (int n = 0; n < 2; ++n) _Pragma("unroll") for (int k = 0; k < 2; ++k) \
;         acc[ai][bj][m][n] = __builtin_amdgcn_mfma_f32_16x16x32_bf16(Bt[n][k], At[m][k], acc[ai][bj][m][n], 0, 0, 0); __builtin_amdgcn_s_setprio(0); } while (0)
; template <class Epi, class Sched, bool ALIGN_EPI = false, bool SP2 = false>
; __device__ __forceinline__ void gemm_phase(PG8_LAS unsigned char* lds, const Gemm g, const Sched& S, const Epi& E, int tid_in) {
;     ...
;             if constexpr (SP2) {
;             PG8_LDB(B0, 0, 0); PG8_LDB(B1, 0, 1); PG8_SCHED; PG8_LDA(At, 0, 0); PG8_STAGE(PG8_SA(1, 1), a1 + hstep, voffA);
;             PG8_WAIT_V(8); PG8_WAIT_L(0); PG8_BAR; PG8_MMA(0, 0, At, B0); PG8_MMA(0, 1, At, B1); PG8_BAR; PG8_SCHED;
;             PG8_LDA(At, 0, 1); PG8_STAGE(PG8_SB(0, 0), b2, voffB); PG8_STAGE(PG8_SB(0, 1), b2 + hstep, voffB); PG8_STAGE(PG8_SA(0, 0), a2, voffA);
;             PG8_WAIT_V(8); PG8_WAIT_L(0); PG8_BAR; PG8_MMA(1, 0, At, B0); PG8_MMA(1, 1, At, B1); PG8_BAR; PG8_SCHED;
;             PG8_LDB(B0, 1, 0); PG8_LDB(B1, 1, 1); PG8_SCHED; PG8_LDA(At, 1, 0); PG8_STAGE(PG8_SA(0, 1), a2 + hstep, voffA);
;             PG8_WAIT_V(8); PG8_WAIT_L(0); PG8_BAR; PG8_MMA(0, 0, At, B0); PG8_MMA(0, 1, At, B1); PG8_BAR; PG8_SCHED;
;             PG8_LDA(At, 1, 1); PG8_STAGE(PG8_SB(1, 0), b3, voffB); PG8_STAGE(PG8_SB(1, 1), b3 + hstep, voffB); PG8_STAGE(PG8_SA(1, 0), a3, voffA);
;             PG8_WAIT_V(8); PG8_WAIT_L(0); PG8_BAR; PG8_MMA(1, 0, At, B0); PG8_MMA(1, 1, At, B1); PG8_BAR; PG8_SCHED;
.LBB0_564:
	s_add_u32 s48, s46, 0xfffc0080
	s_addc_u32 s49, s47, -1
	s_cmp_eq_u32 s52, 12
	s_cselect_b32 s51, s0, s49
	s_cselect_b32 s50, s1, s48
	s_cselect_b32 s49, s7, s45
	s_cselect_b32 s48, s31, s35
	s_add_i32 m0, s59, 0xc000
	ds_read_b128 v[128:131], v180
	global_load_lds_dwordx4 v158, s[46:47]
	s_add_i32 m0, s59, 0xe000
	ds_read_b128 v[132:135], v180 offset:1024
	global_load_lds_dwordx4 v160, s[46:47]
	ds_read_b128 v[136:139], v180 offset:2048
	ds_read_b128 v[140:143], v180 offset:3072
	ds_read_b128 v[166:169], v181
	ds_read_b128 v[170:173], v181 offset:1024
	ds_read_b128 v[174:177], v181 offset:2048
	ds_read_b128 v[184:187], v181 offset:3072
	ds_read_b128 v[188:191], v182
	ds_read_b128 v[192:195], v182 offset:1024
	ds_read_b128 v[196:199], v182 offset:2048
	ds_read_b128 v[200:203], v182 offset:3072
	ds_read_b128 v[204:207], v182 offset:4096
	ds_read_b128 v[208:211], v182 offset:5120
	ds_read_b128 v[212:215], v182 offset:6144
	ds_read_b128 v[216:219], v182 offset:7168
	s_waitcnt vmcnt(8)
	s_waitcnt lgkmcnt(0)
	s_barrier
	v_mfma_f32_16x16x32_bf16 v[68:71], v[128:131], v[188:191], v[68:71]
	v_mfma_f32_16x16x32_bf16 v[56:59], v[136:139], v[188:191], v[56:59]
	v_mfma_f32_16x16x32_bf16 v[52:55], v[128:131], v[196:199], v[52:55]
	v_mfma_f32_16x16x32_bf16 v[48:51], v[136:139], v[196:199], v[48:51]
	v_mfma_f32_16x16x32_bf16 v[44:47], v[128:131], v[204:207], v[44:47]
	v_mfma_f32_16x16x32_bf16 v[40:43], v[136:139], v[204:207], v[40:43]
	v_mfma_f32_16x16x32_bf16 v[36:39], v[128:131], v[212:215], v[36:39]
	v_mfma_f32_16x16x32_bf16 v[32:35], v[136:139], v[212:215], v[32:35]
	v_mfma_f32_16x16x32_bf16 v[68:71], v[132:135], v[192:195], v[68:71]
	v_mfma_f32_16x16x32_bf16 v[56:59], v[140:143], v[192:195], v[56:59]
	v_mfma_f32_16x16x32_bf16 v[52:55], v[132:135], v[200:203], v[52:55]
	v_mfma_f32_16x16x32_bf16 v[48:51], v[140:143], v[200:203], v[48:51]
	v_mfma_f32_16x16x32_bf16 v[44:47], v[132:135], v[208:211], v[44:47]
	v_mfma_f32_16x16x32_bf16 v[40:43], v[140:143], v[208:211], v[40:43]
	v_mfma_f32_16x16x32_bf16 v[36:39], v[132:135], v[216:219], v[36:39]
	v_mfma_f32_16x16x32_bf16 v[32:35], v[140:143], v[216:219], v[32:35]
	v_mfma_f32_16x16x32_bf16 v[124:127], v[166:169], v[188:191], v[124:127]
	v_mfma_f32_16x16x32_bf16 v[120:123], v[174:177], v[188:191], v[120:123]
	v_mfma_f32_16x16x32_bf16 v[116:119], v[166:169], v[196:199], v[116:119]
	v_mfma_f32_16x16x32_bf16 v[112:115], v[174:177], v[196:199], v[112:115]
	v_mfma_f32_16x16x32_bf16 v[108:111], v[166:169], v[204:207], v[108:111]
	v_mfma_f32_16x16x32_bf16 v[104:107], v[174:177], v[204:207], v[104:107]
	v_mfma_f32_16x16x32_bf16 v[100:103], v[166:169], v[212:215], v[100:103]
	v_mfma_f32_16x16x32_bf16 v[96:99], v[174:177], v[212:215], v[96:99]
	v_mfma_f32_16x16x32_bf16 v[124:127], v[170:173], v[192:195], v[124:127]
	v_mfma_f32_16x16x32_bf16 v[120:123], v[184:187], v[192:195], v[120:123]
	v_mfma_f32_16x16x32_bf16 v[116:119], v[170:173], v[200:203], v[116:119]
	v_mfma_f32_16x16x32_bf16 v[112:115], v[184:187], v[200:203], v[112:115]
	v_mfma_f32_16x16x32_bf16 v[108:111], v[170:173], v[208:211], v[108:111]
	v_mfma_f32_16x16x32_bf16 v[104:107], v[184:187], v[208:211], v[104:107]
	v_mfma_f32_16x16x32_bf16 v[100:103], v[170:173], v[216:219], v[100:103]
	v_mfma_f32_16x16x32_bf16 v[96:99], v[184:187], v[216:219], v[96:99]
	s_barrier
	s_add_u32 s98, s48, s14
	s_addc_u32 s99, s49, s15
	s_add_u32 s100, s50, s14
	s_addc_u32 s101, s51, s15
	s_add_i32 s53, s77, s29
	s_mov_b32 m0, s53
	ds_read_b128 v[188:191], v182 offset:16384
	global_load_lds_dwordx4 v146, s[48:49]
	s_add_i32 m0, s53, 0x2000
	s_add_u32 s88, s48, 0x40000
	s_addc_u32 s89, s49, 0
	s_add_i32 s53, s78, s29
	global_load_lds_dwordx4 v150, s[48:49]
	s_mov_b32 m0, s53
	ds_read_b128 v[192:195], v182 offset:17408
	global_load_lds_dwordx4 v146, s[88:89]
	s_add_i32 m0, s53, 0x2000
	ds_read_b128 v[196:199], v182 offset:18432
	global_load_lds_dwordx4 v150, s[88:89]
	s_mov_b32 m0, s59
	ds_read_b128 v[200:203], v182 offset:19456
	global_load_lds_dwordx4 v144, s[50:51]
	s_mov_b32 m0, s60
	ds_read_b128 v[204:207], v182 offset:20480
	global_load_lds_dwordx4 v148, s[50:51]
	ds_read_b128 v[208:211], v182 offset:21504
	ds_read_b128 v[212:215], v182 offset:22528
	ds_read_b128 v[216:219], v182 offset:23552
	s_waitcnt vmcnt(8)
	s_waitcnt lgkmcnt(0)
	s_barrier
	v_mfma_f32_16x16x32_bf16 v[28:31], v[128:131], v[188:191], v[28:31]
	v_mfma_f32_16x16x32_bf16 v[24:27], v[136:139], v[188:191], v[24:27]
	v_mfma_f32_16x16x32_bf16 v[20:23], v[128:131], v[196:199], v[20:23]
	v_mfma_f32_16x16x32_bf16 v[16:19], v[136:139], v[196:199], v[16:19]
	v_mfma_f32_16x16x32_bf16 v[12:15], v[128:131], v[204:207], v[12:15]
	v_mfma_f32_16x16x32_bf16 v[8:11], v[136:139], v[204:207], v[8:11]
	v_mfma_f32_16x16x32_bf16 v[4:7], v[128:131], v[212:215], v[4:7]
	v_mfma_f32_16x16x32_bf16 v[0:3], v[136:139], v[212:215], v[0:3]
	v_mfma_f32_16x16x32_bf16 v[28:31], v[132:135], v[192:195], v[28:31]
	v_mfma_f32_16x16x32_bf16 v[24:27], v[140:143], v[192:195], v[24:27]
	v_mfma_f32_16x16x32_bf16 v[20:23], v[132:135], v[200:203], v[20:23]
	v_mfma_f32_16x16x32_bf16 v[16:19], v[140:143], v[200:203], v[16:19]
	v_mfma_f32_16x16x32_bf16 v[12:15], v[132:135], v[208:211], v[12:15]
	v_mfma_f32_16x16x32_bf16 v[8:11], v[140:143], v[208:211], v[8:11]
	v_mfma_f32_16x16x32_bf16 v[4:7], v[132:135], v[216:219], v[4:7]
	v_mfma_f32_16x16x32_bf16 v[0:3], v[140:143], v[216:219], v[0:3]
	v_mfma_f32_16x16x32_bf16 v[92:95], v[166:169], v[188:191], v[92:95]
	v_mfma_f32_16x16x32_bf16 v[88:91], v[174:177], v[188:191], v[88:91]
	v_mfma_f32_16x16x32_bf16 v[84:87], v[166:169], v[196:199], v[84:87]
	v_mfma_f32_16x16x32_bf16 v[80:83], v[174:177], v[196:199], v[80:83]
	v_mfma_f32_16x16x32_bf16 v[76:79], v[166:169], v[204:207], v[76:79]
	v_mfma_f32_16x16x32_bf16 v[72:75], v[174:177], v[204:207], v[72:75]
	v_mfma_f32_16x16x32_bf16 v[64:67], v[166:169], v[212:215], v[64:67]
	v_mfma_f32_16x16x32_bf16 v[60:63], v[174:177], v[212:215], v[60:63]
	v_mfma_f32_16x16x32_bf16 v[92:95], v[170:173], v[192:195], v[92:95]
	v_mfma_f32_16x16x32_bf16 v[88:91], v[184:187], v[192:195], v[88:91]
	v_mfma_f32_16x16x32_bf16 v[84:87], v[170:173], v[200:203], v[84:87]
	v_mfma_f32_16x16x32_bf16 v[80:83], v[184:187], v[200:203], v[80:83]
	v_mfma_f32_16x16x32_bf16 v[76:79], v[170:173], v[208:211], v[76:79]
	v_mfma_f32_16x16x32_bf16 v[72:75], v[184:187], v[208:211], v[72:75]
	v_mfma_f32_16x16x32_bf16 v[64:67], v[170:173], v[216:219], v[64:67]
	v_mfma_f32_16x16x32_bf16 v[60:63], v[184:187], v[216:219], v[60:63]
	s_barrier
; #define PG8_STAGE(bufoff, gbase, voff) do { _Pragma("unroll") for (int _i = 0; _i < 2; ++_i) \
;         __builtin_amdgcn_global_load_lds((const unsigned*)((const char*)(gbase) + (voff)[_i]), (PG8_LAS unsigned*)(lds + (bufoff) + ldsw + _i * 8192), 16, 0, 0); } while (0)
; #define PG8_WAIT_V(n) asm volatile("s_waitcnt vmcnt(" #n ")" ::: "memory")
; template <class Epi, class Sched, bool ALIGN_EPI = false, bool SP2 = false>
; __device__ __forceinline__ void gemm_phase(PG8_LAS unsigned char* lds, const Gemm g, const Sched& S, const Epi& E, int tid_in) {
;     ...
;             PG8_LDB(B0, 1, 0); PG8_LDB(B1, 1, 1); PG8_SCHED; PG8_LDA(At, 1, 0); PG8_STAGE(PG8_SA(0, 1), a2 + hstep, voffA);
;             PG8_WAIT_V(8); PG8_WAIT_L(0); PG8_BAR; PG8_MMA(0, 0, At, B0); PG8_MMA(0, 1, At, B1); PG8_BAR; PG8_SCHED;
;             PG8_LDA(At, 1, 1); PG8_STAGE(PG8_SB(1, 0), b3, voffB); PG8_STAGE(PG8_SB(1, 1), b3 + hstep, voffB); PG8_STAGE(PG8_SA(1, 0), a3, voffA);
;             PG8_WAIT_V(8); PG8_WAIT_L(0); PG8_BAR; PG8_MMA(1, 0, At, B0); PG8_MMA(1, 1, At, B1); PG8_BAR; PG8_SCHED;
; __device__ __forceinline__ void xcd_barrier(const XcdBarrier& b, int tid) {
;     asm volatile("s_waitcnt vmcnt(0)" ::: "memory");
;     __syncthreads();
;     if (tid == 0) {
;         unsigned* bar = b.bar;
;         __builtin_amdgcn_s_waitcnt(0);
;         unsigned nloc = b.st[0], nx = b.st[1];
;         if (nloc == 0u) { xcd_barrier_complete(bar, b.x, nloc, nx); b.st[0] = nloc; b.st[1] = nx; }
;         const unsigned old = xb_add(&bar[XB_XSUB(b.x)], 1u);
;         const unsigned gen = old / nloc;
;         if (old + 1u == (gen + 1u) * nloc) {
;             __builtin_amdgcn_fence(__ATOMIC_RELEASE, "agent");
;             asm volatile("s_waitcnt vmcnt(0)" ::: "memory");
;             const unsigned og = xb_add(&bar[XB_TOP], 1u);
;             const unsigned tg = og / nx;
;             if (og + 1u == (tg + 1u) * nx) xb_add(&bar[XB_TOPGEN], 1u);
;             else XB_SPIN(xb_ld(&bar[XB_TOPGEN]) == tg, bar);
;             __builtin_amdgcn_fence(__ATOMIC_ACQUIRE, "agent");
;             xb_add(&bar[XB_XGEN(b.x)], 1u);
;             asm volatile("s_waitcnt vmcnt(0)" ::: "memory");
;         } else {
;             XB_SPIN(xb_ld(&bar[XB_XGEN(b.x)]) == gen, bar);
;             __builtin_amdgcn_fence(__ATOMIC_ACQUIRE, "agent");
;             asm volatile("s_waitcnt vmcnt(0)" ::: "memory");
;         }
	s_add_i32 s53, 0, 0x18000
	s_add_i32 s88, 0, 0x1c000
	s_add_u32 s50, s50, 0x40000
	s_addc_u32 s51, s51, 0
	s_mov_b32 m0, s61
	s_nop 0
	global_load_lds_dwordx4 v144, s[50:51]
	s_mov_b32 m0, s62
	s_nop 0
	global_load_lds_dwordx4 v148, s[50:51]
	v_add_u32_e32 v140, s53, v179
	v_add_u32_e32 v184, s88, v179
	ds_read_b128 v[128:131], v140
	ds_read_b128 v[132:135], v140 offset:1024
	ds_read_b128 v[136:139], v140 offset:2048
	ds_read_b128 v[140:143], v140 offset:3072
	ds_read_b128 v[166:169], v184
	ds_read_b128 v[170:173], v184 offset:1024
	ds_read_b128 v[174:177], v184 offset:2048
	ds_read_b128 v[184:187], v184 offset:3072
	ds_read_b128 v[188:191], v182 offset:32768
	ds_read_b128 v[192:195], v182 offset:33792
	ds_read_b128 v[196:199], v182 offset:34816
	ds_read_b128 v[200:203], v182 offset:35840
	ds_read_b128 v[204:207], v182 offset:36864
	ds_read_b128 v[208:211], v182 offset:37888
	ds_read_b128 v[212:215], v182 offset:38912
	ds_read_b128 v[216:219], v182 offset:39936
	s_waitcnt vmcnt(8)
	s_waitcnt lgkmcnt(0)
	s_barrier
	v_mfma_f32_16x16x32_bf16 v[68:71], v[128:131], v[188:191], v[68:71]
	v_mfma_f32_16x16x32_bf16 v[56:59], v[136:139], v[188:191], v[56:59]
	v_mfma_f32_16x16x32_bf16 v[52:55], v[128:131], v[196:199], v[52:55]
	v_mfma_f32_16x16x32_bf16 v[48:51], v[136:139], v[196:199], v[48:51]
	v_mfma_f32_16x16x32_bf16 v[44:47], v[128:131], v[204:207], v[44:47]
	v_mfma_f32_16x16x32_bf16 v[40:43], v[136:139], v[204:207], v[40:43]
	v_mfma_f32_16x16x32_bf16 v[36:39], v[128:131], v[212:215], v[36:39]
	v_mfma_f32_16x16x32_bf16 v[32:35], v[136:139], v[212:215], v[32:35]
	v_mfma_f32_16x16x32_bf16 v[68:71], v[132:135], v[192:195], v[68:71]
	v_mfma_f32_16x16x32_bf16 v[56:59], v[140:143], v[192:195], v[56:59]
	v_mfma_f32_16x16x32_bf16 v[52:55], v[132:135], v[200:203], v[52:55]
	v_mfma_f32_16x16x32_bf16 v[48:51], v[140:143], v[200:203], v[48:51]
	v_mfma_f32_16x16x32_bf16 v[44:47], v[132:135], v[208:211], v[44:47]
	v_mfma_f32_16x16x32_bf16 v[40:43], v[140:143], v[208:211], v[40:43]
	v_mfma_f32_16x16x32_bf16 v[36:39], v[132:135], v[216:219], v[36:39]
	v_mfma_f32_16x16x32_bf16 v[32:35], v[140:143], v[216:219], v[32:35]
	v_mfma_f32_16x16x32_bf16 v[124:127], v[166:169], v[188:191], v[124:127]
	v_mfma_f32_16x16x32_bf16 v[120:123], v[174:177], v[188:191], v[120:123]
	v_mfma_f32_16x16x32_bf16 v[116:119], v[166:169], v[196:199], v[116:119]
	v_mfma_f32_16x16x32_bf16 v[112:115], v[174:177], v[196:199], v[112:115]
	v_mfma_f32_16x16x32_bf16 v[108:111], v[166:169], v[204:207], v[108:111]
	v_mfma_f32_16x16x32_bf16 v[104:107], v[174:177], v[204:207], v[104:107]
	v_mfma_f32_16x16x32_bf16 v[100:103], v[166:169], v[212:215], v[100:103]
	v_mfma_f32_16x16x32_bf16 v[96:99], v[174:177], v[212:215], v[96:99]
	v_mfma_f32_16x16x32_bf16 v[124:127], v[170:173], v[192:195], v[124:127]
	v_mfma_f32_16x16x32_bf16 v[120:123], v[184:187], v[192:195], v[120:123]
	v_mfma_f32_16x16x32_bf16 v[116:119], v[170:173], v[200:203], v[116:119]
	v_mfma_f32_16x16x32_bf16 v[112:115], v[184:187], v[200:203], v[112:115]
	v_mfma_f32_16x16x32_bf16 v[108:111], v[170:173], v[208:211], v[108:111]
	v_mfma_f32_16x16x32_bf16 v[104:107], v[184:187], v[208:211], v[104:107]
	v_mfma_f32_16x16x32_bf16 v[100:103], v[170:173], v[216:219], v[100:103]
	v_mfma_f32_16x16x32_bf16 v[96:99], v[184:187], v[216:219], v[96:99]
	s_barrier
	s_add_i32 s50, s53, s29
	s_mov_b32 m0, s50
	ds_read_b128 v[188:191], v182 offset:49152
	global_load_lds_dwordx4 v146, s[98:99]
	s_add_i32 m0, s50, 0x2000
	s_add_u32 s48, s48, 0x40080
	s_addc_u32 s49, s49, 0
	s_add_i32 s50, s88, s29
	global_load_lds_dwordx4 v150, s[98:99]
	s_mov_b32 m0, s50
	ds_read_b128 v[192:195], v182 offset:50176
	global_load_lds_dwordx4 v146, s[48:49]
	s_add_i32 m0, s50, 0x2000
	ds_read_b128 v[196:199], v182 offset:51200
	global_load_lds_dwordx4 v150, s[48:49]
	s_mov_b32 m0, s63
	ds_read_b128 v[200:203], v182 offset:52224
	global_load_lds_dwordx4 v144, s[100:101]
	s_mov_b32 m0, s64
	ds_read_b128 v[204:207], v182 offset:53248
	global_load_lds_dwordx4 v148, s[100:101]
	ds_read_b128 v[208:211], v182 offset:54272
	ds_read_b128 v[212:215], v182 offset:55296
	ds_read_b128 v[216:219], v182 offset:56320
	s_waitcnt vmcnt(8)
	s_waitcnt lgkmcnt(0)
	s_barrier
	v_mfma_f32_16x16x32_bf16 v[28:31], v[128:131], v[188:191], v[28:31]
	v_mfma_f32_16x16x32_bf16 v[24:27], v[136:139], v[188:191], v[24:27]
	v_mfma_f32_16x16x32_bf16 v[20:23], v[128:131], v[196:199], v[20:23]
	v_mfma_f32_16x16x32_bf16 v[16:19], v[136:139], v[196:199], v[16:19]
	v_mfma_f32_16x16x32_bf16 v[12:15], v[128:131], v[204:207], v[12:15]
	v_mfma_f32_16x16x32_bf16 v[8:11], v[136:139], v[204:207], v[8:11]
	v_mfma_f32_16x16x32_bf16 v[4:7], v[128:131], v[212:215], v[4:7]
	v_mfma_f32_16x16x32_bf16 v[0:3], v[136:139], v[212:215], v[0:3]
	v_mfma_f32_16x16x32_bf16 v[28:31], v[132:135], v[192:195], v[28:31]
	v_mfma_f32_16x16x32_bf16 v[24:27], v[140:143], v[192:195], v[24:27]
	v_mfma_f32_16x16x32_bf16 v[20:23], v[132:135], v[200:203], v[20:23]
	v_mfma_f32_16x16x32_bf16 v[16:19], v[140:143], v[200:203], v[16:19]
	v_mfma_f32_16x16x32_bf16 v[12:15], v[132:135], v[208:211], v[12:15]
	v_mfma_f32_16x16x32_bf16 v[8:11], v[140:143], v[208:211], v[8:11]
	v_mfma_f32_16x16x32_bf16 v[4:7], v[132:135], v[216:219], v[4:7]
	v_mfma_f32_16x16x32_bf16 v[0:3], v[140:143], v[216:219], v[0:3]
	v_mfma_f32_16x16x32_bf16 v[92:95], v[166:169], v[188:191], v[92:95]
	v_mfma_f32_16x16x32_bf16 v[88:91], v[174:177], v[188:191], v[88:91]
	v_mfma_f32_16x16x32_bf16 v[84:87], v[166:169], v[196:199], v[84:87]
	v_mfma_f32_16x16x32_bf16 v[80:83], v[174:177], v[196:199], v[80:83]
	v_mfma_f32_16x16x32_bf16 v[76:79], v[166:169], v[204:207], v[76:79]
	v_mfma_f32_16x16x32_bf16 v[72:75], v[174:177], v[204:207], v[72:75]
	v_mfma_f32_16x16x32_bf16 v[64:67], v[166:169], v[212:215], v[64:67]
	v_mfma_f32_16x16x32_bf16 v[60:63], v[174:177], v[212:215], v[60:63]
	v_mfma_f32_16x16x32_bf16 v[92:95], v[170:173], v[192:195], v[92:95]
	v_mfma_f32_16x16x32_bf16 v[88:91], v[184:187], v[192:195], v[88:91]
	v_mfma_f32_16x16x32_bf16 v[84:87], v[170:173], v[200:203], v[84:87]
	v_mfma_f32_16x16x32_bf16 v[80:83], v[184:187], v[200:203], v[80:83]
	v_mfma_f32_16x16x32_bf16 v[76:79], v[170:173], v[208:211], v[76:79]
	v_mfma_f32_16x16x32_bf16 v[72:75], v[184:187], v[208:211], v[72:75]
	v_mfma_f32_16x16x32_bf16 v[64:67], v[170:173], v[216:219], v[64:67]
	v_mfma_f32_16x16x32_bf16 v[60:63], v[184:187], v[216:219], v[60:63]
	s_barrier
	s_add_i32 s52, s52, 2
	s_add_u32 s46, s46, 0x100
	s_addc_u32 s47, s47, 0
	s_add_u32 s35, s35, 0x100
	s_addc_u32 s45, s45, 0
	s_cmp_gt_u32 s52, 13
	s_cbranch_scc0 .LBB0_564
	s_cmp_eq_u32 s86, 1
	s_cbranch_scc0 .Lww_done_p3
	v_readlane_b32 s98, v248, 0
	s_nop 3
	s_cmp_eq_u32 s98, 0
	s_cbranch_scc0 .Lww_bar_p3
	v_readlane_b32 s98, v248, 32
	s_nop 3
	s_cmp_eq_u32 s98, 1
	s_cbranch_scc0 .Lww_bar_p3
	v_readfirstlane_b32 s99, v247
	s_nop 3
	s_cmp_ge_u32 s99, 2
	s_cbranch_scc1 .Lww_bar_p3
	v_mov_b32_e32 v246, 0x3500
	s_mov_b32 s98, 0

; #define MYTID() (wave_s * 64 + (int)__builtin_amdgcn_mbcnt_hi(~0u, __builtin_amdgcn_mbcnt_lo(~0u, 0u)))
;     __host__ __device__ bool next(int i, Unit& u) const {
;         const long L = (long)i * G + c; if (L >= nwg) return false;
;         int wgid = (int)L; { const int q = nwg / NXCD, r = nwg % NXCD, xcd = wgid % NXCD, off = wgid / NXCD; wgid = (xcd < r ? xcd * (q + 1) : r * (q + 1) + (xcd - r) * q) + off; }
;         const int nig = WGM * nN, gid = wgid / nig, fm = gid * WGM, gsz = (nM - fm) < WGM ? (nM - fm) : WGM;
;         u.pm = fm + ((wgid % nig) % gsz); u.pn = (wgid % nig) / gsz; u.ord = i; return true;
; __global__ void __launch_bounds__(NTHREADS, 2) fwd_kernel(Args a) {
;     ...
;     if (IN(6)) { pg8::Gemm g{(const bf16_t*)(ws + WS_OC), (const bf16_t*)(ws + WS_WON), MTOK, DM, DM}; pg8::StaticOrder S; S.init(MTOK, DM, G, bx); pg8::EpiGateF E{P_MERGED, P_GM};
;         pg8::gemm_phase<pg8::EpiGateF, pg8::StaticOrder, true, true>(lds, g, S, E, MYTID()); }
.LBB0_1044:
	s_cmp_lt_i32 s42, 7
	s_cselect_b64 s[0:1], -1, 0
	s_cmp_gt_i32 s43, 6
	s_cselect_b64 s[2:3], -1, 0
	s_and_b64 s[4:5], s[0:1], s[2:3]
	s_andn2_b64 vcc, exec, s[4:5]
	s_cbranch_vccnz .LBB0_1074
	v_mov_b32_e32 v246, 0x3500
	global_load_dword v247, v246, s[40:41] sc1
	v_mbcnt_hi_u32_b32 v0, -1, v230
	v_readlane_b32 s0, v248, 0
	s_cmpk_gt_i32 s33, 0x1ff
	s_waitcnt lgkmcnt(0)
	v_add_u32_e32 v1, s0, v0
	s_nop 0
	v_readfirstlane_b32 s0, v1
	s_cbranch_scc1 .LBB0_1074
	s_ashr_i32 s52, s33, 31
	s_lshr_b32 s1, s52, 29
	s_add_i32 s1, s33, s1
	s_and_b32 s2, s1, -8
	s_sub_i32 s7, s33, s2
	s_cmp_gt_i32 s7, -1
	s_cbranch_scc0 .LBB0_1048
	s_lshl_b32 s6, s7, 6
	s_cbranch_execz .LBB0_1049
	s_branch .LBB0_1050

; #define PG8_BAR __builtin_amdgcn_s_barrier()
; __device__ __forceinline__ unsigned xb_ld(unsigned* p)              { return __hip_atomic_load(p, __ATOMIC_RELAXED, __HIP_MEMORY_SCOPE_AGENT); }
; __device__ __forceinline__ unsigned xb_add(unsigned* p, unsigned v) { return __hip_atomic_fetch_add(p, v, __ATOMIC_RELAXED, __HIP_MEMORY_SCOPE_AGENT); }
; #define XB_SPIN(cond, bar) do { unsigned _sp = 0; while (cond) { __builtin_amdgcn_s_sleep(1); \
;     if ((++_sp & 255u) == 0u) { if (xb_ld(&(bar)[XB_TMO])) break; if (_sp > XB_SPIN_CAP) { atomicAdd(&(bar)[XB_TMO], 1u); break; } } } } while (0)
; template <class Epi, class Sched, bool ALIGN_EPI = false, bool SP2 = false>
; __device__ __forceinline__ void gemm_phase(PG8_LAS unsigned char* lds, const Gemm g, const Sched& S, const Epi& E, int tid_in) {
;     ...
;         for (int t = 0; t < nt; t += 2) {
;             if constexpr (Epi::MIDK) { if (t == Epi::MIDK_T) { if (wr == 0) PG8_BAR; E.mid(acc, cur, wr, wc, fr, fq); if (wr == 1) PG8_BAR; } }
;             const bool last = (t == nt - 2);
; __device__ __forceinline__ void xcd_barrier(const XcdBarrier& b, int tid) {
;     asm volatile("s_waitcnt vmcnt(0)" ::: "memory");
;     __syncthreads();
;     if (tid == 0) {
;         unsigned* bar = b.bar;
;         __builtin_amdgcn_s_waitcnt(0);
;         unsigned nloc = b.st[0], nx = b.st[1];
;         if (nloc == 0u) { xcd_barrier_complete(bar, b.x, nloc, nx); b.st[0] = nloc; b.st[1] = nx; }
;         const unsigned old = xb_add(&bar[XB_XSUB(b.x)], 1u);
;         const unsigned gen = old / nloc;
;         if (old + 1u == (gen + 1u) * nloc) {
;             __builtin_amdgcn_fence(__ATOMIC_RELEASE, "agent");
;             asm volatile("s_waitcnt vmcnt(0)" ::: "memory");
;             const unsigned og = xb_add(&bar[XB_TOP], 1u);
;             const unsigned tg = og / nx;
;             if (og + 1u == (tg + 1u) * nx) xb_add(&bar[XB_TOPGEN], 1u);
;             else XB_SPIN(xb_ld(&bar[XB_TOPGEN]) == tg, bar);
;             __builtin_amdgcn_fence(__ATOMIC_ACQUIRE, "agent");
;             xb_add(&bar[XB_XGEN(b.x)], 1u);
;             asm volatile("s_waitcnt vmcnt(0)" ::: "memory");
;         } else {
;             XB_SPIN(xb_ld(&bar[XB_XGEN(b.x)]) == gen, bar);
;             __builtin_amdgcn_fence(__ATOMIC_ACQUIRE, "agent");
;             asm volatile("s_waitcnt vmcnt(0)" ::: "memory");
;         }
.LBB0_1063:
	s_cmpk_lg_i32 s46, 0x400
	s_cbranch_scc1 .LBB0_1062
	s_cmp_eq_u32 s62, 1
	s_cbranch_scc0 .Lww_done_p6
	v_readlane_b32 s98, v248, 0
	s_nop 3
	s_cmp_eq_u32 s98, 0
	s_cbranch_scc0 .Lww_bar_p6
	v_readlane_b32 s98, v248, 32
	s_nop 3
	s_cmp_eq_u32 s98, 1
	s_cbranch_scc0 .Lww_bar_p6
	v_readfirstlane_b32 s99, v247
	s_nop 3
	s_cmp_ge_u32 s99, 3
	s_cbranch_scc1 .Lww_bar_p6
	v_mov_b32_e32 v246, 0x3500
	s_mov_b32 s98, 0

; #define GEMM_SWIGLU(k, WOFF) if (IN(k)) { pg8::Gemm g{P_XB, (const bf16_t*)(ws + (WOFF)), MTOK, NUP, DM}; pg8::StaticOrder S; S.init(MTOK, NUP, G, bx); pg8::EpiSwiGLU E{P_HB, DFF, (k) == 1 ? (const LAS float*)nullptr : (const LAS float*)(lds + RT_OFF)}; if ((k) != 1) FILL_ROW_SCALES(NUP); \
;         pg8::gemm_phase<pg8::EpiSwiGLU, pg8::StaticOrder, true, true>(lds, g, S, E, MYTID()); }
; __global__ void __launch_bounds__(NTHREADS, 2) fwd_kernel(Args a) {
;     ...
;     GEMM_SWIGLU(9, WS_WUP2)
.LBB0_1225:
	s_cmp_lt_i32 s42, 10
	s_cselect_b64 s[0:1], -1, 0
	s_and_b64 s[4:5], s[0:1], s[2:3]
	s_andn2_b64 vcc, exec, s[4:5]
	s_cbranch_vccnz .LBB0_1245
	v_mov_b32_e32 v246, 0x3500
	global_load_dword v247, v246, s[40:41] sc1
	v_mbcnt_hi_u32_b32 v0, -1, v230
	v_readlane_b32 s0, v248, 0
	s_sub_i32 s1, s66, s33
	s_add_i32 s2, s1, 0xaff
	v_add_u32_e32 v8, s0, v0
	s_abs_i32 s0, s66
	s_waitcnt lgkmcnt(0)
	v_cvt_f32_u32_e32 v1, s0
	s_sub_i32 s1, 0xfffff501, s1
	s_xor_b32 s3, s2, s66
	s_max_i32 s1, s2, s1
	v_rcp_iflag_f32_e32 v1, v1
	s_sub_i32 s2, 0, s0
	s_ashr_i32 s3, s3, 31
	v_mov_b32_e32 v0, v8
	v_mul_f32_e32 v1, 0x4f7ffffe, v1
	v_cvt_u32_f32_e32 v1, v1
	s_nop 0
	v_readfirstlane_b32 s6, v1
	s_mul_i32 s2, s2, s6
	s_mul_hi_u32 s2, s6, s2
	s_add_i32 s6, s6, s2
	s_mul_hi_u32 s2, s1, s6
	s_mul_i32 s6, s2, s0
	s_sub_i32 s1, s1, s6
	s_add_i32 s6, s2, 1
	s_sub_i32 s7, s1, s0
	s_cmp_ge_u32 s1, s0
	s_cselect_b32 s2, s6, s2
	s_cselect_b32 s1, s7, s1
	s_add_i32 s6, s2, 1
	s_cmp_ge_u32 s1, s0
	s_cselect_b32 s0, s6, s2
	s_xor_b32 s0, s0, s3
	s_sub_i32 s0, s0, s3
	s_lshl_b32 s0, s0, 8
	v_cmp_gt_i32_e32 vcc, s0, v0
	s_and_saveexec_b64 s[2:3], vcc
	s_cbranch_execz .LBB0_1229
	s_add_u32 s6, s40, 0x3400000
	v_lshl_add_u32 v2, v0, 2, 0
	s_addc_u32 s7, s41, 0
	v_and_b32_e32 v1, 0xff, v0
	v_add_u32_e32 v2, 0x20100, v2
	s_mov_b64 s[8:9], 0
	v_mov_b32_e32 v3, 0x160
	v_mov_b32_e32 v4, 0x161
	s_mov_b32 s1, 0x2e8ba2e9
	s_movk_i32 s10, 0x58
	v_mov_b32_e32 v5, 0x358637bd
	s_mov_b64 s[14:15], 0
	s_mov_b64 s[16:17], 0
	s_mov_b64 s[22:23], 0
	s_mov_b64 s[24:25], 0
	s_mov_b64 s[26:27], 0
	s_mov_b64 s[98:99], 0
	v_mov_b32_e32 v122, v2
	s_mov_b64 s[14:15], exec
	v_ashrrev_i32_e32 v6, 8, v0
	v_mul_lo_u32 v6, v6, s66
	v_add_u32_e32 v7, s33, v6
	v_ashrrev_i32_e32 v6, 31, v7
	v_lshrrev_b32_e32 v6, 29, v6
	v_add_u32_e32 v9, v7, v6
	v_ashrrev_i32_e32 v6, 3, v9
	v_and_b32_e32 v9, -8, v9
	v_sub_u32_e32 v7, v7, v9
	v_cmp_gt_i32_e32 vcc, 0, v7
	v_add_u32_e32 v0, 0x200, v0
	s_nop 0
	v_cndmask_b32_e32 v9, v3, v4, vcc
	v_mad_u64_u32 v[6:7], s[12:13], v7, v9, v[6:7]
	v_mul_hi_i32 v7, v6, s1
	v_lshrrev_b32_e32 v9, 31, v7
	v_ashrrev_i32_e32 v7, 4, v7
	v_add_u32_e32 v7, v7, v9
	v_lshlrev_b32_e32 v9, 2, v7
	v_mul_lo_u32 v7, v7, s10
	v_sub_u32_e32 v10, 0x80, v9
	v_sub_u32_e32 v6, v6, v7
	v_min_i32_e32 v7, 4, v10
	v_sub_u32_e32 v11, 0, v6
	v_ashrrev_i32_e32 v10, 31, v6
	v_max_i32_e32 v6, v6, v11
	v_sub_u32_e32 v11, 0, v7
	v_max_i32_e32 v7, v7, v11
	v_cvt_f32_u32_e32 v11, v7
	v_sub_u32_e32 v12, 0, v7
	v_rcp_iflag_f32_e32 v11, v11
	s_nop 0
	v_mul_f32_e32 v11, 0x4f7ffffe, v11
	v_cvt_u32_f32_e32 v11, v11
	v_mul_lo_u32 v12, v12, v11
	v_mul_hi_u32 v12, v11, v12
	v_add_u32_e32 v11, v11, v12
	v_mul_hi_u32 v11, v6, v11
	v_mul_lo_u32 v11, v11, v7
	v_sub_u32_e32 v6, v6, v11
	v_sub_u32_e32 v11, v6, v7
	v_cmp_ge_u32_e32 vcc, v6, v7
	s_nop 1
	v_cndmask_b32_e32 v6, v6, v11, vcc
	v_sub_u32_e32 v11, v6, v7
	v_cmp_ge_u32_e32 vcc, v6, v7
	s_nop 1
	v_cndmask_b32_e32 v6, v6, v11, vcc
	v_xor_b32_e32 v6, v6, v10
	v_sub_u32_e32 v6, v6, v10
	v_add_u32_e32 v6, v9, v6
	v_lshl_or_b32 v6, v6, 8, v1
	v_ashrrev_i32_e32 v7, 31, v6
	v_lshlrev_b64 v[6:7], 6, v[6:7]
	v_lshl_add_u64 v[6:7], s[6:7], 0, v[6:7]
	global_load_dwordx4 v[26:29], v[6:7], off
	global_load_dwordx4 v[30:33], v[6:7], off offset:32
	global_load_dwordx4 v[34:37], v[6:7], off offset:16
	global_load_dwordx4 v[38:41], v[6:7], off offset:48
	v_cmp_le_i32_e32 vcc, s0, v0
	s_or_b64 s[8:9], vcc, s[8:9]
	s_andn2_b64 exec, exec, s[8:9]
	s_cbranch_execz .Lfrs_wait_p9
	s_mov_b64 s[16:17], exec
	v_ashrrev_i32_e32 v6, 8, v0
	v_mul_lo_u32 v6, v6, s66
	v_add_u32_e32 v7, s33, v6
	v_ashrrev_i32_e32 v6, 31, v7
	v_lshrrev_b32_e32 v6, 29, v6
	v_add_u32_e32 v9, v7, v6
	v_ashrrev_i32_e32 v6, 3, v9
	v_and_b32_e32 v9, -8, v9
	v_sub_u32_e32 v7, v7, v9
	v_cmp_gt_i32_e32 vcc, 0, v7
	v_add_u32_e32 v0, 0x200, v0
	s_nop 0
	v_cndmask_b32_e32 v9, v3, v4, vcc
	v_mad_u64_u32 v[6:7], s[12:13], v7, v9, v[6:7]
	v_mul_hi_i32 v7, v6, s1
	v_lshrrev_b32_e32 v9, 31, v7
	v_ashrrev_i32_e32 v7, 4, v7
	v_add_u32_e32 v7, v7, v9
	v_lshlrev_b32_e32 v9, 2, v7
	v_mul_lo_u32 v7, v7, s10
	v_sub_u32_e32 v10, 0x80, v9
	v_sub_u32_e32 v6, v6, v7
	v_min_i32_e32 v7, 4, v10
	v_sub_u32_e32 v11, 0, v6
	v_ashrrev_i32_e32 v10, 31, v6
	v_max_i32_e32 v6, v6, v11
	v_sub_u32_e32 v11, 0, v7
	v_max_i32_e32 v7, v7, v11
	v_cvt_f32_u32_e32 v11, v7
	v_sub_u32_e32 v12, 0, v7
	v_rcp_iflag_f32_e32 v11, v11
	s_nop 0
	v_mul_f32_e32 v11, 0x4f7ffffe, v11
	v_cvt_u32_f32_e32 v11, v11
	v_mul_lo_u32 v12, v12, v11
	v_mul_hi_u32 v12, v11, v12
	v_add_u32_e32 v11, v11, v12
	v_mul_hi_u32 v11, v6, v11
	v_mul_lo_u32 v11, v11, v7
	v_sub_u32_e32 v6, v6, v11
	v_sub_u32_e32 v11, v6, v7
	v_cmp_ge_u32_e32 vcc, v6, v7
	s_nop 1
	v_cndmask_b32_e32 v6, v6, v11, vcc
	v_sub_u32_e32 v11, v6, v7
	v_cmp_ge_u32_e32 vcc, v6, v7
	s_nop 1
	v_cndmask_b32_e32 v6, v6, v11, vcc
	v_xor_b32_e32 v6, v6, v10
	v_sub_u32_e32 v6, v6, v10
	v_add_u32_e32 v6, v9, v6
	v_lshl_or_b32 v6, v6, 8, v1
	v_ashrrev_i32_e32 v7, 31, v6
	v_lshlrev_b64 v[6:7], 6, v[6:7]
	v_lshl_add_u64 v[6:7], s[6:7], 0, v[6:7]
	global_load_dwordx4 v[42:45], v[6:7], off
	global_load_dwordx4 v[46:49], v[6:7], off offset:32
	global_load_dwordx4 v[50:53], v[6:7], off offset:16
	global_load_dwordx4 v[54:57], v[6:7], off offset:48
	v_cmp_le_i32_e32 vcc, s0, v0
	s_or_b64 s[8:9], vcc, s[8:9]
	s_andn2_b64 exec, exec, s[8:9]
	s_cbranch_execz .Lfrs_wait_p9
	s_mov_b64 s[22:23], exec
	v_ashrrev_i32_e32 v6, 8, v0
	v_mul_lo_u32 v6, v6, s66
	v_add_u32_e32 v7, s33, v6
	v_ashrrev_i32_e32 v6, 31, v7
	v_lshrrev_b32_e32 v6, 29, v6
	v_add_u32_e32 v9, v7, v6
	v_ashrrev_i32_e32 v6, 3, v9
	v_and_b32_e32 v9, -8, v9
	v_sub_u32_e32 v7, v7, v9
	v_cmp_gt_i32_e32 vcc, 0, v7
	v_add_u32_e32 v0, 0x200, v0
	s_nop 0
	v_cndmask_b32_e32 v9, v3, v4, vcc
	v_mad_u64_u32 v[6:7], s[12:13], v7, v9, v[6:7]
	v_mul_hi_i32 v7, v6, s1
	v_lshrrev_b32_e32 v9, 31, v7
	v_ashrrev_i32_e32 v7, 4, v7
	v_add_u32_e32 v7, v7, v9
	v_lshlrev_b32_e32 v9, 2, v7
	v_mul_lo_u32 v7, v7, s10
	v_sub_u32_e32 v10, 0x80, v9
	v_sub_u32_e32 v6, v6, v7
	v_min_i32_e32 v7, 4, v10
	v_sub_u32_e32 v11, 0, v6
	v_ashrrev_i32_e32 v10, 31, v6
	v_max_i32_e32 v6, v6, v11
	v_sub_u32_e32 v11, 0, v7
	v_max_i32_e32 v7, v7, v11
	v_cvt_f32_u32_e32 v11, v7
	v_sub_u32_e32 v12, 0, v7
	v_rcp_iflag_f32_e32 v11, v11
	s_nop 0
	v_mul_f32_e32 v11, 0x4f7ffffe, v11
	v_cvt_u32_f32_e32 v11, v11
	v_mul_lo_u32 v12, v12, v11
	v_mul_hi_u32 v12, v11, v12
	v_add_u32_e32 v11, v11, v12
	v_mul_hi_u32 v11, v6, v11
	v_mul_lo_u32 v11, v11, v7
	v_sub_u32_e32 v6, v6, v11
	v_sub_u32_e32 v11, v6, v7
	v_cmp_ge_u32_e32 vcc, v6, v7
	s_nop 1
	v_cndmask_b32_e32 v6, v6, v11, vcc
	v_sub_u32_e32 v11, v6, v7
	v_cmp_ge_u32_e32 vcc, v6, v7
	s_nop 1
	v_cndmask_b32_e32 v6, v6, v11, vcc
	v_xor_b32_e32 v6, v6, v10
	v_sub_u32_e32 v6, v6, v10
	v_add_u32_e32 v6, v9, v6
	v_lshl_or_b32 v6, v6, 8, v1
	v_ashrrev_i32_e32 v7, 31, v6
	v_lshlrev_b64 v[6:7], 6, v[6:7]
	v_lshl_add_u64 v[6:7], s[6:7], 0, v[6:7]
	global_load_dwordx4 v[58:61], v[6:7], off
	global_load_dwordx4 v[62:65], v[6:7], off offset:32
	global_load_dwordx4 v[66:69], v[6:7], off offset:16
	global_load_dwordx4 v[70:73], v[6:7], off offset:48
	v_cmp_le_i32_e32 vcc, s0, v0
	s_or_b64 s[8:9], vcc, s[8:9]
	s_andn2_b64 exec, exec, s[8:9]
	s_cbranch_execz .Lfrs_wait_p9
	s_mov_b64 s[24:25], exec
	v_ashrrev_i32_e32 v6, 8, v0
	v_mul_lo_u32 v6, v6, s66
	v_add_u32_e32 v7, s33, v6
	v_ashrrev_i32_e32 v6, 31, v7
	v_lshrrev_b32_e32 v6, 29, v6
	v_add_u32_e32 v9, v7, v6
	v_ashrrev_i32_e32 v6, 3, v9
	v_and_b32_e32 v9, -8, v9
	v_sub_u32_e32 v7, v7, v9
	v_cmp_gt_i32_e32 vcc, 0, v7
	v_add_u32_e32 v0, 0x200, v0
	s_nop 0
	v_cndmask_b32_e32 v9, v3, v4, vcc
	v_mad_u64_u32 v[6:7], s[12:13], v7, v9, v[6:7]
	v_mul_hi_i32 v7, v6, s1
	v_lshrrev_b32_e32 v9, 31, v7
	v_ashrrev_i32_e32 v7, 4, v7
	v_add_u32_e32 v7, v7, v9
	v_lshlrev_b32_e32 v9, 2, v7
	v_mul_lo_u32 v7, v7, s10
	v_sub_u32_e32 v10, 0x80, v9
	v_sub_u32_e32 v6, v6, v7
	v_min_i32_e32 v7, 4, v10
	v_sub_u32_e32 v11, 0, v6
	v_ashrrev_i32_e32 v10, 31, v6
	v_max_i32_e32 v6, v6, v11
	v_sub_u32_e32 v11, 0, v7
	v_max_i32_e32 v7, v7, v11
	v_cvt_f32_u32_e32 v11, v7
	v_sub_u32_e32 v12, 0, v7
	v_rcp_iflag_f32_e32 v11, v11
	s_nop 0
	v_mul_f32_e32 v11, 0x4f7ffffe, v11
	v_cvt_u32_f32_e32 v11, v11
	v_mul_lo_u32 v12, v12, v11
	v_mul_hi_u32 v12, v11, v12
	v_add_u32_e32 v11, v11, v12
	v_mul_hi_u32 v11, v6, v11
	v_mul_lo_u32 v11, v11, v7
	v_sub_u32_e32 v6, v6, v11
	v_sub_u32_e32 v11, v6, v7
	v_cmp_ge_u32_e32 vcc, v6, v7
	s_nop 1
	v_cndmask_b32_e32 v6, v6, v11, vcc
	v_sub_u32_e32 v11, v6, v7
	v_cmp_ge_u32_e32 vcc, v6, v7
	s_nop 1
	v_cndmask_b32_e32 v6, v6, v11, vcc
	v_xor_b32_e32 v6, v6, v10
	v_sub_u32_e32 v6, v6, v10
	v_add_u32_e32 v6, v9, v6
	v_lshl_or_b32 v6, v6, 8, v1
	v_ashrrev_i32_e32 v7, 31, v6
	v_lshlrev_b64 v[6:7], 6, v[6:7]
	v_lshl_add_u64 v[6:7], s[6:7], 0, v[6:7]
	global_load_dwordx4 v[74:77], v[6:7], off
	global_load_dwordx4 v[78:81], v[6:7], off offset:32
	global_load_dwordx4 v[82:85], v[6:7], off offset:16
	global_load_dwordx4 v[86:89], v[6:7], off offset:48
	v_cmp_le_i32_e32 vcc, s0, v0
	s_or_b64 s[8:9], vcc, s[8:9]
	s_andn2_b64 exec, exec, s[8:9]
	s_cbranch_execz .Lfrs_wait_p9
	s_mov_b64 s[26:27], exec
	v_ashrrev_i32_e32 v6, 8, v0
	v_mul_lo_u32 v6, v6, s66
	v_add_u32_e32 v7, s33, v6
	v_ashrrev_i32_e32 v6, 31, v7
	v_lshrrev_b32_e32 v6, 29, v6
	v_add_u32_e32 v9, v7, v6
	v_ashrrev_i32_e32 v6, 3, v9
	v_and_b32_e32 v9, -8, v9
	v_sub_u32_e32 v7, v7, v9
	v_cmp_gt_i32_e32 vcc, 0, v7
	v_add_u32_e32 v0, 0x200, v0
	s_nop 0
	v_cndmask_b32_e32 v9, v3, v4, vcc
	v_mad_u64_u32 v[6:7], s[12:13], v7, v9, v[6:7]
	v_mul_hi_i32 v7, v6, s1
	v_lshrrev_b32_e32 v9, 31, v7
	v_ashrrev_i32_e32 v7, 4, v7
	v_add_u32_e32 v7, v7, v9
	v_lshlrev_b32_e32 v9, 2, v7
	v_mul_lo_u32 v7, v7, s10
	v_sub_u32_e32 v10, 0x80, v9
	v_sub_u32_e32 v6, v6, v7
	v_min_i32_e32 v7, 4, v10
	v_sub_u32_e32 v11, 0, v6
	v_ashrrev_i32_e32 v10, 31, v6
	v_max_i32_e32 v6, v6, v11
	v_sub_u32_e32 v11, 0, v7
	v_max_i32_e32 v7, v7, v11
	v_cvt_f32_u32_e32 v11, v7
	v_sub_u32_e32 v12, 0, v7
	v_rcp_iflag_f32_e32 v11, v11
	s_nop 0
	v_mul_f32_e32 v11, 0x4f7ffffe, v11
	v_cvt_u32_f32_e32 v11, v11
	v_mul_lo_u32 v12, v12, v11
	v_mul_hi_u32 v12, v11, v12
	v_add_u32_e32 v11, v11, v12
	v_mul_hi_u32 v11, v6, v11
	v_mul_lo_u32 v11, v11, v7
	v_sub_u32_e32 v6, v6, v11
	v_sub_u32_e32 v11, v6, v7
	v_cmp_ge_u32_e32 vcc, v6, v7
	s_nop 1
	v_cndmask_b32_e32 v6, v6, v11, vcc
	v_sub_u32_e32 v11, v6, v7
	v_cmp_ge_u32_e32 vcc, v6, v7
	s_nop 1
	v_cndmask_b32_e32 v6, v6, v11, vcc
	v_xor_b32_e32 v6, v6, v10
	v_sub_u32_e32 v6, v6, v10
	v_add_u32_e32 v6, v9, v6
	v_lshl_or_b32 v6, v6, 8, v1
	v_ashrrev_i32_e32 v7, 31, v6
	v_lshlrev_b64 v[6:7], 6, v[6:7]
	v_lshl_add_u64 v[6:7], s[6:7], 0, v[6:7]
	global_load_dwordx4 v[90:93], v[6:7], off
	global_load_dwordx4 v[94:97], v[6:7], off offset:32
	global_load_dwordx4 v[98:101], v[6:7], off offset:16
	global_load_dwordx4 v[102:105], v[6:7], off offset:48
	v_cmp_le_i32_e32 vcc, s0, v0
	s_or_b64 s[8:9], vcc, s[8:9]
	s_andn2_b64 exec, exec, s[8:9]
	s_cbranch_execz .Lfrs_wait_p9
	s_mov_b64 s[98:99], exec
	v_ashrrev_i32_e32 v6, 8, v0
	v_mul_lo_u32 v6, v6, s66
	v_add_u32_e32 v7, s33, v6
	v_ashrrev_i32_e32 v6, 31, v7
	v_lshrrev_b32_e32 v6, 29, v6
	v_add_u32_e32 v9, v7, v6
	v_ashrrev_i32_e32 v6, 3, v9
	v_and_b32_e32 v9, -8, v9
	v_sub_u32_e32 v7, v7, v9
	v_cmp_gt_i32_e32 vcc, 0, v7
	v_add_u32_e32 v0, 0x200, v0
	s_nop 0
	v_cndmask_b32_e32 v9, v3, v4, vcc
	v_mad_u64_u32 v[6:7], s[12:13], v7, v9, v[6:7]
	v_mul_hi_i32 v7, v6, s1
	v_lshrrev_b32_e32 v9, 31, v7
	v_ashrrev_i32_e32 v7, 4, v7
	v_add_u32_e32 v7, v7, v9
	v_lshlrev_b32_e32 v9, 2, v7
	v_mul_lo_u32 v7, v7, s10
	v_sub_u32_e32 v10, 0x80, v9
	v_sub_u32_e32 v6, v6, v7
	v_min_i32_e32 v7, 4, v10
	v_sub_u32_e32 v11, 0, v6
	v_ashrrev_i32_e32 v10, 31, v6
	v_max_i32_e32 v6, v6, v11
	v_sub_u32_e32 v11, 0, v7
	v_max_i32_e32 v7, v7, v11
	v_cvt_f32_u32_e32 v11, v7
	v_sub_u32_e32 v12, 0, v7
	v_rcp_iflag_f32_e32 v11, v11
	s_nop 0
	v_mul_f32_e32 v11, 0x4f7ffffe, v11
	v_cvt_u32_f32_e32 v11, v11
	v_mul_lo_u32 v12, v12, v11
	v_mul_hi_u32 v12, v11, v12
	v_add_u32_e32 v11, v11, v12
	v_mul_hi_u32 v11, v6, v11
	v_mul_lo_u32 v11, v11, v7
	v_sub_u32_e32 v6, v6, v11
	v_sub_u32_e32 v11, v6, v7
	v_cmp_ge_u32_e32 vcc, v6, v7
	s_nop 1
	v_cndmask_b32_e32 v6, v6, v11, vcc
	v_sub_u32_e32 v11, v6, v7
	v_cmp_ge_u32_e32 vcc, v6, v7
	s_nop 1
	v_cndmask_b32_e32 v6, v6, v11, vcc
	v_xor_b32_e32 v6, v6, v10
	v_sub_u32_e32 v6, v6, v10
	v_add_u32_e32 v6, v9, v6
	v_lshl_or_b32 v6, v6, 8, v1
	v_ashrrev_i32_e32 v7, 31, v6
	v_lshlrev_b64 v[6:7], 6, v[6:7]
	v_lshl_add_u64 v[6:7], s[6:7], 0, v[6:7]
	global_load_dwordx4 v[106:109], v[6:7], off
	global_load_dwordx4 v[110:113], v[6:7], off offset:32
	global_load_dwordx4 v[114:117], v[6:7], off offset:16
	global_load_dwordx4 v[118:121], v[6:7], off offset:48
	v_cmp_le_i32_e32 vcc, s0, v0
	s_or_b64 s[8:9], vcc, s[8:9]
	s_andn2_b64 exec, exec, s[8:9]

; #define PG8_STAGE(bufoff, gbase, voff) do { _Pragma("unroll") for (int _i = 0; _i < 2; ++_i) \
;         __builtin_amdgcn_global_load_lds((const unsigned*)((const char*)(gbase) + (voff)[_i]), (PG8_LAS unsigned*)(lds + (bufoff) + ldsw + _i * 8192), 16, 0, 0); } while (0)
; #define PG8_LDA(dst, b, h) do { _Pragma("unroll") for (int m = 0; m < 4; ++m) _Pragma("unroll") for (int k = 0; k < 2; ++k) dst[m][k] = *(const PG8_LAS bf16x8*)(lds + PG8_SA(b, h) + aoff + m * 2048 + k * 1024); } while (0)
; #define PG8_LDB(dst, b, h) do { _Pragma("unroll") for (int n = 0; n < 2; ++n) _Pragma("unroll") for (int k = 0; k < 2; ++k) dst[n][k] = *(const PG8_LAS bf16x8*)(lds + PG8_SB(b, h) + boff + n * 2048 + k * 1024); } while (0)
; #define PG8_MMA(ai, bj, At, Bt) do { __builtin_amdgcn_s_setprio(1); _Pragma("unroll") for (int m = 0; m < 4; ++m) _Pragma("unroll") for (int n = 0; n < 2; ++n) _Pragma("unroll") for (int k = 0; k < 2; ++k) \
;         acc[ai][bj][m][n] = __builtin_amdgcn_mfma_f32_16x16x32_bf16(Bt[n][k], At[m][k], acc[ai][bj][m][n], 0, 0, 0); __builtin_amdgcn_s_setprio(0); } while (0)
; template <class Epi, class Sched, bool ALIGN_EPI = false, bool SP2 = false>
; __device__ __forceinline__ void gemm_phase(PG8_LAS unsigned char* lds, const Gemm g, const Sched& S, const Epi& E, int tid_in) {
;     ...
;             if constexpr (SP2) {
;             PG8_LDB(B0, 0, 0); PG8_LDB(B1, 0, 1); PG8_SCHED; PG8_LDA(At, 0, 0); PG8_STAGE(PG8_SA(1, 1), a1 + hstep, voffA);
;             PG8_WAIT_V(8); PG8_WAIT_L(0); PG8_BAR; PG8_MMA(0, 0, At, B0); PG8_MMA(0, 1, At, B1); PG8_BAR; PG8_SCHED;
;             PG8_LDA(At, 0, 1); PG8_STAGE(PG8_SB(0, 0), b2, voffB); PG8_STAGE(PG8_SB(0, 1), b2 + hstep, voffB); PG8_STAGE(PG8_SA(0, 0), a2, voffA);
;             PG8_WAIT_V(8); PG8_WAIT_L(0); PG8_BAR; PG8_MMA(1, 0, At, B0); PG8_MMA(1, 1, At, B1); PG8_BAR; PG8_SCHED;
;             PG8_LDB(B0, 1, 0); PG8_LDB(B1, 1, 1); PG8_SCHED; PG8_LDA(At, 1, 0); PG8_STAGE(PG8_SA(0, 1), a2 + hstep, voffA);
;             PG8_WAIT_V(8); PG8_WAIT_L(0); PG8_BAR; PG8_MMA(0, 0, At, B0); PG8_MMA(0, 1, At, B1); PG8_BAR; PG8_SCHED;
;             PG8_LDA(At, 1, 1); PG8_STAGE(PG8_SB(1, 0), b3, voffB); PG8_STAGE(PG8_SB(1, 1), b3 + hstep, voffB); PG8_STAGE(PG8_SA(1, 0), a3, voffA);
;             PG8_WAIT_V(8); PG8_WAIT_L(0); PG8_BAR; PG8_MMA(1, 0, At, B0); PG8_MMA(1, 1, At, B1); PG8_BAR; PG8_SCHED;
.LBB0_1238:
	s_add_u32 s26, s24, 0xfffc0080
	s_addc_u32 s27, s25, -1
	s_cmp_eq_u32 s58, 12
	s_cselect_b32 s29, s17, s27
	s_cselect_b32 s28, s54, s26
	s_cselect_b32 s27, s15, s57
	s_cselect_b32 s26, s55, s56
	s_add_i32 m0, s23, 0xc000
	ds_read_b128 v[144:147], v154
	global_load_lds_dwordx4 v136, s[24:25]
	s_add_i32 m0, s23, 0xe000
	ds_read_b128 v[158:161], v154 offset:1024
	global_load_lds_dwordx4 v138, s[24:25]
	ds_read_b128 v[162:165], v154 offset:2048
	ds_read_b128 v[166:169], v154 offset:3072
	ds_read_b128 v[170:173], v155
	ds_read_b128 v[174:177], v155 offset:1024
	ds_read_b128 v[178:181], v155 offset:2048
	ds_read_b128 v[182:185], v155 offset:3072
	ds_read_b128 v[186:189], v156
	ds_read_b128 v[190:193], v156 offset:1024
	ds_read_b128 v[194:197], v156 offset:2048
	ds_read_b128 v[198:201], v156 offset:3072
	ds_read_b128 v[202:205], v156 offset:4096
	ds_read_b128 v[206:209], v156 offset:5120
	ds_read_b128 v[210:213], v156 offset:6144
	ds_read_b128 v[214:217], v156 offset:7168
	s_waitcnt vmcnt(8)
	s_waitcnt lgkmcnt(0)
	s_barrier
	v_mfma_f32_16x16x32_bf16 v[124:127], v[144:147], v[186:189], v[124:127]
	v_mfma_f32_16x16x32_bf16 v[120:123], v[162:165], v[186:189], v[120:123]
	v_mfma_f32_16x16x32_bf16 v[108:111], v[144:147], v[194:197], v[108:111]
	v_mfma_f32_16x16x32_bf16 v[104:107], v[162:165], v[194:197], v[104:107]
	v_mfma_f32_16x16x32_bf16 v[92:95], v[144:147], v[202:205], v[92:95]
	v_mfma_f32_16x16x32_bf16 v[88:91], v[162:165], v[202:205], v[88:91]
	v_mfma_f32_16x16x32_bf16 v[76:79], v[144:147], v[210:213], v[76:79]
	v_mfma_f32_16x16x32_bf16 v[72:75], v[162:165], v[210:213], v[72:75]
	v_mfma_f32_16x16x32_bf16 v[124:127], v[158:161], v[190:193], v[124:127]
	v_mfma_f32_16x16x32_bf16 v[120:123], v[166:169], v[190:193], v[120:123]
	v_mfma_f32_16x16x32_bf16 v[108:111], v[158:161], v[198:201], v[108:111]
	v_mfma_f32_16x16x32_bf16 v[104:107], v[166:169], v[198:201], v[104:107]
	v_mfma_f32_16x16x32_bf16 v[92:95], v[158:161], v[206:209], v[92:95]
	v_mfma_f32_16x16x32_bf16 v[88:91], v[166:169], v[206:209], v[88:91]
	v_mfma_f32_16x16x32_bf16 v[76:79], v[158:161], v[214:217], v[76:79]
	v_mfma_f32_16x16x32_bf16 v[72:75], v[166:169], v[214:217], v[72:75]
	v_mfma_f32_16x16x32_bf16 v[116:119], v[170:173], v[186:189], v[116:119]
	v_mfma_f32_16x16x32_bf16 v[112:115], v[178:181], v[186:189], v[112:115]
	v_mfma_f32_16x16x32_bf16 v[100:103], v[170:173], v[194:197], v[100:103]
	v_mfma_f32_16x16x32_bf16 v[96:99], v[178:181], v[194:197], v[96:99]
	v_mfma_f32_16x16x32_bf16 v[84:87], v[170:173], v[202:205], v[84:87]
	v_mfma_f32_16x16x32_bf16 v[80:83], v[178:181], v[202:205], v[80:83]
	v_mfma_f32_16x16x32_bf16 v[68:71], v[170:173], v[210:213], v[68:71]
	v_mfma_f32_16x16x32_bf16 v[64:67], v[178:181], v[210:213], v[64:67]
	v_mfma_f32_16x16x32_bf16 v[116:119], v[174:177], v[190:193], v[116:119]
	v_mfma_f32_16x16x32_bf16 v[112:115], v[182:185], v[190:193], v[112:115]
	v_mfma_f32_16x16x32_bf16 v[100:103], v[174:177], v[198:201], v[100:103]
	v_mfma_f32_16x16x32_bf16 v[96:99], v[182:185], v[198:201], v[96:99]
	v_mfma_f32_16x16x32_bf16 v[84:87], v[174:177], v[206:209], v[84:87]
	v_mfma_f32_16x16x32_bf16 v[80:83], v[182:185], v[206:209], v[80:83]
	v_mfma_f32_16x16x32_bf16 v[68:71], v[174:177], v[214:217], v[68:71]
	v_mfma_f32_16x16x32_bf16 v[64:67], v[182:185], v[214:217], v[64:67]
	s_barrier
	s_add_u32 s98, s26, s10
	s_addc_u32 s99, s27, s11
	s_add_u32 s100, s28, s10
	s_addc_u32 s101, s29, s11
	s_add_i32 s59, s47, s0
	s_mov_b32 m0, s59
	ds_read_b128 v[186:189], v156 offset:16384
	global_load_lds_dwordx4 v132, s[26:27]
	s_add_i32 m0, s59, 0x2000
	s_add_u32 s60, s26, 0x40000
	s_addc_u32 s61, s27, 0
	s_add_i32 s59, s48, s0
	global_load_lds_dwordx4 v128, s[26:27]
	s_mov_b32 m0, s59
	ds_read_b128 v[190:193], v156 offset:17408
	global_load_lds_dwordx4 v132, s[60:61]
	s_add_i32 m0, s59, 0x2000
	ds_read_b128 v[194:197], v156 offset:18432
	global_load_lds_dwordx4 v128, s[60:61]
	s_mov_b32 m0, s23
	ds_read_b128 v[198:201], v156 offset:19456
	global_load_lds_dwordx4 v134, s[28:29]
	s_mov_b32 m0, s37
	ds_read_b128 v[202:205], v156 offset:20480
	global_load_lds_dwordx4 v130, s[28:29]
	ds_read_b128 v[206:209], v156 offset:21504
	ds_read_b128 v[210:213], v156 offset:22528
	ds_read_b128 v[214:217], v156 offset:23552
	s_waitcnt vmcnt(8)
	s_waitcnt lgkmcnt(0)
	s_barrier
	v_mfma_f32_16x16x32_bf16 v[60:63], v[144:147], v[186:189], v[60:63]
	v_mfma_f32_16x16x32_bf16 v[56:59], v[162:165], v[186:189], v[56:59]
	v_mfma_f32_16x16x32_bf16 v[44:47], v[144:147], v[194:197], v[44:47]
	v_mfma_f32_16x16x32_bf16 v[40:43], v[162:165], v[194:197], v[40:43]
	v_mfma_f32_16x16x32_bf16 v[28:31], v[144:147], v[202:205], v[28:31]
	v_mfma_f32_16x16x32_bf16 v[24:27], v[162:165], v[202:205], v[24:27]
	v_mfma_f32_16x16x32_bf16 v[12:15], v[144:147], v[210:213], v[12:15]
	v_mfma_f32_16x16x32_bf16 v[8:11], v[162:165], v[210:213], v[8:11]
	v_mfma_f32_16x16x32_bf16 v[60:63], v[158:161], v[190:193], v[60:63]
	v_mfma_f32_16x16x32_bf16 v[56:59], v[166:169], v[190:193], v[56:59]
	v_mfma_f32_16x16x32_bf16 v[44:47], v[158:161], v[198:201], v[44:47]
	v_mfma_f32_16x16x32_bf16 v[40:43], v[166:169], v[198:201], v[40:43]
	v_mfma_f32_16x16x32_bf16 v[28:31], v[158:161], v[206:209], v[28:31]
	v_mfma_f32_16x16x32_bf16 v[24:27], v[166:169], v[206:209], v[24:27]
	v_mfma_f32_16x16x32_bf16 v[12:15], v[158:161], v[214:217], v[12:15]
	v_mfma_f32_16x16x32_bf16 v[8:11], v[166:169], v[214:217], v[8:11]
	v_mfma_f32_16x16x32_bf16 v[52:55], v[170:173], v[186:189], v[52:55]
	v_mfma_f32_16x16x32_bf16 v[48:51], v[178:181], v[186:189], v[48:51]
	v_mfma_f32_16x16x32_bf16 v[36:39], v[170:173], v[194:197], v[36:39]
	v_mfma_f32_16x16x32_bf16 v[32:35], v[178:181], v[194:197], v[32:35]
	v_mfma_f32_16x16x32_bf16 v[20:23], v[170:173], v[202:205], v[20:23]
	v_mfma_f32_16x16x32_bf16 v[16:19], v[178:181], v[202:205], v[16:19]
	v_mfma_f32_16x16x32_bf16 v[4:7], v[170:173], v[210:213], v[4:7]
	v_mfma_f32_16x16x32_bf16 v[0:3], v[178:181], v[210:213], v[0:3]
	v_mfma_f32_16x16x32_bf16 v[52:55], v[174:177], v[190:193], v[52:55]
	v_mfma_f32_16x16x32_bf16 v[48:51], v[182:185], v[190:193], v[48:51]
	v_mfma_f32_16x16x32_bf16 v[36:39], v[174:177], v[198:201], v[36:39]
	v_mfma_f32_16x16x32_bf16 v[32:35], v[182:185], v[198:201], v[32:35]
	v_mfma_f32_16x16x32_bf16 v[20:23], v[174:177], v[206:209], v[20:23]
	v_mfma_f32_16x16x32_bf16 v[16:19], v[182:185], v[206:209], v[16:19]
	v_mfma_f32_16x16x32_bf16 v[4:7], v[174:177], v[214:217], v[4:7]
	v_mfma_f32_16x16x32_bf16 v[0:3], v[182:185], v[214:217], v[0:3]
	s_barrier
; #define PG8_STAGE(bufoff, gbase, voff) do { _Pragma("unroll") for (int _i = 0; _i < 2; ++_i) \
;         __builtin_amdgcn_global_load_lds((const unsigned*)((const char*)(gbase) + (voff)[_i]), (PG8_LAS unsigned*)(lds + (bufoff) + ldsw + _i * 8192), 16, 0, 0); } while (0)
; #define PG8_WAIT_V(n) asm volatile("s_waitcnt vmcnt(" #n ")" ::: "memory")
; template <class Epi, class Sched, bool ALIGN_EPI = false, bool SP2 = false>
; __device__ __forceinline__ void gemm_phase(PG8_LAS unsigned char* lds, const Gemm g, const Sched& S, const Epi& E, int tid_in) {
;     ...
;             PG8_LDB(B0, 1, 0); PG8_LDB(B1, 1, 1); PG8_SCHED; PG8_LDA(At, 1, 0); PG8_STAGE(PG8_SA(0, 1), a2 + hstep, voffA);
;             PG8_WAIT_V(8); PG8_WAIT_L(0); PG8_BAR; PG8_MMA(0, 0, At, B0); PG8_MMA(0, 1, At, B1); PG8_BAR; PG8_SCHED;
;             PG8_LDA(At, 1, 1); PG8_STAGE(PG8_SB(1, 0), b3, voffB); PG8_STAGE(PG8_SB(1, 1), b3 + hstep, voffB); PG8_STAGE(PG8_SA(1, 0), a3, voffA);
;             PG8_WAIT_V(8); PG8_WAIT_L(0); PG8_BAR; PG8_MMA(1, 0, At, B0); PG8_MMA(1, 1, At, B1); PG8_BAR; PG8_SCHED;
; __device__ __forceinline__ void xcd_barrier(const XcdBarrier& b, int tid) {
;     asm volatile("s_waitcnt vmcnt(0)" ::: "memory");
;     __syncthreads();
;     if (tid == 0) {
;         unsigned* bar = b.bar;
;         __builtin_amdgcn_s_waitcnt(0);
;         unsigned nloc = b.st[0], nx = b.st[1];
;         if (nloc == 0u) { xcd_barrier_complete(bar, b.x, nloc, nx); b.st[0] = nloc; b.st[1] = nx; }
;         const unsigned old = xb_add(&bar[XB_XSUB(b.x)], 1u);
;         const unsigned gen = old / nloc;
;         if (old + 1u == (gen + 1u) * nloc) {
;             __builtin_amdgcn_fence(__ATOMIC_RELEASE, "agent");
;             asm volatile("s_waitcnt vmcnt(0)" ::: "memory");
;             const unsigned og = xb_add(&bar[XB_TOP], 1u);
;             const unsigned tg = og / nx;
;             if (og + 1u == (tg + 1u) * nx) xb_add(&bar[XB_TOPGEN], 1u);
;             else XB_SPIN(xb_ld(&bar[XB_TOPGEN]) == tg, bar);
;             __builtin_amdgcn_fence(__ATOMIC_ACQUIRE, "agent");
;             xb_add(&bar[XB_XGEN(b.x)], 1u);
;             asm volatile("s_waitcnt vmcnt(0)" ::: "memory");
;         } else {
;             XB_SPIN(xb_ld(&bar[XB_XGEN(b.x)]) == gen, bar);
;             __builtin_amdgcn_fence(__ATOMIC_ACQUIRE, "agent");
;             asm volatile("s_waitcnt vmcnt(0)" ::: "memory");
;         }
	s_add_i32 s59, 0, 0x18000
	s_add_i32 s60, 0, 0x1c000
	s_add_u32 s28, s28, 0x40000
	s_addc_u32 s29, s29, 0
	s_mov_b32 m0, s38
	v_add_u32_e32 v157, s59, v151
	global_load_lds_dwordx4 v134, s[28:29]
	s_mov_b32 m0, s39
	ds_read_b128 v[144:147], v157
	global_load_lds_dwordx4 v130, s[28:29]
	ds_read_b128 v[158:161], v157 offset:1024
	ds_read_b128 v[162:165], v157 offset:2048
	ds_read_b128 v[166:169], v157 offset:3072
	v_add_u32_e32 v157, s60, v151
	ds_read_b128 v[170:173], v157
	ds_read_b128 v[174:177], v157 offset:1024
	ds_read_b128 v[178:181], v157 offset:2048
	ds_read_b128 v[182:185], v157 offset:3072
	ds_read_b128 v[186:189], v156 offset:32768
	ds_read_b128 v[190:193], v156 offset:33792
	ds_read_b128 v[194:197], v156 offset:34816
	ds_read_b128 v[198:201], v156 offset:35840
	ds_read_b128 v[202:205], v156 offset:36864
	ds_read_b128 v[206:209], v156 offset:37888
	ds_read_b128 v[210:213], v156 offset:38912
	ds_read_b128 v[214:217], v156 offset:39936
	s_waitcnt vmcnt(8)
	s_waitcnt lgkmcnt(0)
	s_barrier
	v_mfma_f32_16x16x32_bf16 v[124:127], v[144:147], v[186:189], v[124:127]
	v_mfma_f32_16x16x32_bf16 v[120:123], v[162:165], v[186:189], v[120:123]
	v_mfma_f32_16x16x32_bf16 v[108:111], v[144:147], v[194:197], v[108:111]
	v_mfma_f32_16x16x32_bf16 v[104:107], v[162:165], v[194:197], v[104:107]
	v_mfma_f32_16x16x32_bf16 v[92:95], v[144:147], v[202:205], v[92:95]
	v_mfma_f32_16x16x32_bf16 v[88:91], v[162:165], v[202:205], v[88:91]
	v_mfma_f32_16x16x32_bf16 v[76:79], v[144:147], v[210:213], v[76:79]
	v_mfma_f32_16x16x32_bf16 v[72:75], v[162:165], v[210:213], v[72:75]
	v_mfma_f32_16x16x32_bf16 v[124:127], v[158:161], v[190:193], v[124:127]
	v_mfma_f32_16x16x32_bf16 v[120:123], v[166:169], v[190:193], v[120:123]
	v_mfma_f32_16x16x32_bf16 v[108:111], v[158:161], v[198:201], v[108:111]
	v_mfma_f32_16x16x32_bf16 v[104:107], v[166:169], v[198:201], v[104:107]
	v_mfma_f32_16x16x32_bf16 v[92:95], v[158:161], v[206:209], v[92:95]
	v_mfma_f32_16x16x32_bf16 v[88:91], v[166:169], v[206:209], v[88:91]
	v_mfma_f32_16x16x32_bf16 v[76:79], v[158:161], v[214:217], v[76:79]
	v_mfma_f32_16x16x32_bf16 v[72:75], v[166:169], v[214:217], v[72:75]
	v_mfma_f32_16x16x32_bf16 v[116:119], v[170:173], v[186:189], v[116:119]
	v_mfma_f32_16x16x32_bf16 v[112:115], v[178:181], v[186:189], v[112:115]
	v_mfma_f32_16x16x32_bf16 v[100:103], v[170:173], v[194:197], v[100:103]
	v_mfma_f32_16x16x32_bf16 v[96:99], v[178:181], v[194:197], v[96:99]
	v_mfma_f32_16x16x32_bf16 v[84:87], v[170:173], v[202:205], v[84:87]
	v_mfma_f32_16x16x32_bf16 v[80:83], v[178:181], v[202:205], v[80:83]
	v_mfma_f32_16x16x32_bf16 v[68:71], v[170:173], v[210:213], v[68:71]
	v_mfma_f32_16x16x32_bf16 v[64:67], v[178:181], v[210:213], v[64:67]
	v_mfma_f32_16x16x32_bf16 v[116:119], v[174:177], v[190:193], v[116:119]
	v_mfma_f32_16x16x32_bf16 v[112:115], v[182:185], v[190:193], v[112:115]
	v_mfma_f32_16x16x32_bf16 v[100:103], v[174:177], v[198:201], v[100:103]
	v_mfma_f32_16x16x32_bf16 v[96:99], v[182:185], v[198:201], v[96:99]
	v_mfma_f32_16x16x32_bf16 v[84:87], v[174:177], v[206:209], v[84:87]
	v_mfma_f32_16x16x32_bf16 v[80:83], v[182:185], v[206:209], v[80:83]
	v_mfma_f32_16x16x32_bf16 v[68:71], v[174:177], v[214:217], v[68:71]
	v_mfma_f32_16x16x32_bf16 v[64:67], v[182:185], v[214:217], v[64:67]
	s_barrier
	s_add_i32 s28, s59, s0
	s_mov_b32 m0, s28
	ds_read_b128 v[186:189], v156 offset:49152
	global_load_lds_dwordx4 v132, s[98:99]
	s_add_i32 m0, s28, 0x2000
	s_add_u32 s26, s26, 0x40080
	s_addc_u32 s27, s27, 0
	s_add_i32 s28, s60, s0
	global_load_lds_dwordx4 v128, s[98:99]
	s_mov_b32 m0, s28
	ds_read_b128 v[190:193], v156 offset:50176
	global_load_lds_dwordx4 v132, s[26:27]
	s_add_i32 m0, s28, 0x2000
	ds_read_b128 v[194:197], v156 offset:51200
	global_load_lds_dwordx4 v128, s[26:27]
	s_mov_b32 m0, s44
	ds_read_b128 v[198:201], v156 offset:52224
	global_load_lds_dwordx4 v134, s[100:101]
	s_mov_b32 m0, s45
	ds_read_b128 v[202:205], v156 offset:53248
	global_load_lds_dwordx4 v130, s[100:101]
	ds_read_b128 v[206:209], v156 offset:54272
	ds_read_b128 v[210:213], v156 offset:55296
	ds_read_b128 v[214:217], v156 offset:56320
	s_waitcnt vmcnt(8)
	s_waitcnt lgkmcnt(0)
	s_barrier
	v_mfma_f32_16x16x32_bf16 v[60:63], v[144:147], v[186:189], v[60:63]
	v_mfma_f32_16x16x32_bf16 v[56:59], v[162:165], v[186:189], v[56:59]
	v_mfma_f32_16x16x32_bf16 v[44:47], v[144:147], v[194:197], v[44:47]
	v_mfma_f32_16x16x32_bf16 v[40:43], v[162:165], v[194:197], v[40:43]
	v_mfma_f32_16x16x32_bf16 v[28:31], v[144:147], v[202:205], v[28:31]
	v_mfma_f32_16x16x32_bf16 v[24:27], v[162:165], v[202:205], v[24:27]
	v_mfma_f32_16x16x32_bf16 v[12:15], v[144:147], v[210:213], v[12:15]
	v_mfma_f32_16x16x32_bf16 v[8:11], v[162:165], v[210:213], v[8:11]
	v_mfma_f32_16x16x32_bf16 v[60:63], v[158:161], v[190:193], v[60:63]
	v_mfma_f32_16x16x32_bf16 v[56:59], v[166:169], v[190:193], v[56:59]
	v_mfma_f32_16x16x32_bf16 v[44:47], v[158:161], v[198:201], v[44:47]
	v_mfma_f32_16x16x32_bf16 v[40:43], v[166:169], v[198:201], v[40:43]
	v_mfma_f32_16x16x32_bf16 v[28:31], v[158:161], v[206:209], v[28:31]
	v_mfma_f32_16x16x32_bf16 v[24:27], v[166:169], v[206:209], v[24:27]
	v_mfma_f32_16x16x32_bf16 v[12:15], v[158:161], v[214:217], v[12:15]
	v_mfma_f32_16x16x32_bf16 v[8:11], v[166:169], v[214:217], v[8:11]
	v_mfma_f32_16x16x32_bf16 v[52:55], v[170:173], v[186:189], v[52:55]
	v_mfma_f32_16x16x32_bf16 v[48:51], v[178:181], v[186:189], v[48:51]
	v_mfma_f32_16x16x32_bf16 v[36:39], v[170:173], v[194:197], v[36:39]
	v_mfma_f32_16x16x32_bf16 v[32:35], v[178:181], v[194:197], v[32:35]
	v_mfma_f32_16x16x32_bf16 v[20:23], v[170:173], v[202:205], v[20:23]
	v_mfma_f32_16x16x32_bf16 v[16:19], v[178:181], v[202:205], v[16:19]
	v_mfma_f32_16x16x32_bf16 v[4:7], v[170:173], v[210:213], v[4:7]
	v_mfma_f32_16x16x32_bf16 v[0:3], v[178:181], v[210:213], v[0:3]
	v_mfma_f32_16x16x32_bf16 v[52:55], v[174:177], v[190:193], v[52:55]
	v_mfma_f32_16x16x32_bf16 v[48:51], v[182:185], v[190:193], v[48:51]
	v_mfma_f32_16x16x32_bf16 v[36:39], v[174:177], v[198:201], v[36:39]
	v_mfma_f32_16x16x32_bf16 v[32:35], v[182:185], v[198:201], v[32:35]
	v_mfma_f32_16x16x32_bf16 v[20:23], v[174:177], v[206:209], v[20:23]
	v_mfma_f32_16x16x32_bf16 v[16:19], v[182:185], v[206:209], v[16:19]
	v_mfma_f32_16x16x32_bf16 v[4:7], v[174:177], v[214:217], v[4:7]
	v_mfma_f32_16x16x32_bf16 v[0:3], v[182:185], v[214:217], v[0:3]
	s_barrier
	s_add_i32 s58, s58, 2
	s_add_u32 s24, s24, 0x100
	s_addc_u32 s25, s25, 0
	s_add_u32 s56, s56, 0x100
	s_addc_u32 s57, s57, 0
	s_cmp_gt_u32 s58, 13
	s_cbranch_scc0 .LBB0_1238
	s_cmp_eq_u32 s50, 1
	s_cbranch_scc0 .Lww_done_p9
	v_readlane_b32 s98, v248, 0
	s_nop 3
	s_cmp_eq_u32 s98, 0
	s_cbranch_scc0 .Lww_bar_p9
	v_readlane_b32 s98, v248, 32
	s_nop 3
	s_cmp_eq_u32 s98, 1
	s_cbranch_scc0 .Lww_bar_p9
	v_readfirstlane_b32 s99, v247
	s_nop 3
	s_cmp_ge_u32 s99, 4
	s_cbranch_scc1 .Lww_bar_p9
	v_mov_b32_e32 v246, 0x3500
	s_mov_b32 s98, 0
